# attention unit epilogue: the 16 gate (z) loads were each issued one step ahead and waited on at once (16 serialized latencies per unit); all issued up front into free VGPRs with counted vmcnt; on comb
# speedup vs baseline: 1.0052x; 1.0046x over previous
; __device__ __forceinline__ unsigned cvt_pk_bf16(float lo, float hi) { unsigned r; asm volatile("v_cvt_pk_bf16_f32 %0, %1, %2" : "=v"(r) : "v"(lo), "v"(hi)); return r; }
;     template <class T> __device__ __forceinline__ T* w(size_t off) const { return (T*)(pp->ws + off); }
; __device__ __forceinline__ float bf2f(unsigned b) { return __uint_as_float(b << 16); }
; __device__ __forceinline__ void dsa_attn_unit(const Ctx& c, int l, int b, int kvh, int qb64) {
;     ...
;     const float inv = 1.0f / l_run;
;     const bf16* ZC = c.w<bf16>(WS_ZC) + (size_t)row * 1024 + hq * 128;
;     bf16* MX = c.w<bf16>(WS_MIX) + (size_t)row * DM + 3072 + hq * 128;
; #pragma unroll
;     for (int mt = 0; mt < 4; ++mt)
; #pragma unroll
;         for (int v4 = 0; v4 < 4; ++v4) {
;             const int d = 32 * mt + 8 * v4 + 4 * hf;
;             const u32x2 z = *(const u32x2*)(ZC + d);
;             u32x2 w;
;             w.x = pg8::cvt_pk_bf16(O[mt][4 * v4 + 0] * inv * bf2f(z.x & 0xffffu), O[mt][4 * v4 + 1] * inv * bf2f(z.x >> 16));
;             w.y = pg8::cvt_pk_bf16(O[mt][4 * v4 + 2] * inv * bf2f(z.y & 0xffffu), O[mt][4 * v4 + 3] * inv * bf2f(z.y >> 16));
;             *(u32x2*)(MX + d) = w;
;         }
.LBB0_1451:
	v_lshl_add_u64 v[64:65], v[160:161], 1, s[0:1]
	s_lshl_b64 s[2:3], s[2:3], 1
	v_ashrrev_i32_e32 v169, 31, v168
	v_lshl_add_u64 v[64:65], v[64:65], 0, s[2:3]
	v_lshlrev_b64 v[68:69], 1, v[168:169]
	v_lshl_add_u64 v[64:65], v[64:65], 0, v[68:69]
	v_add_co_u32_e32 v66, vcc, s83, v64
	v_lshlrev_b32_e32 v160, 13, v166
	s_nop 0
	v_addc_co_u32_e32 v67, vcc, 0, v65, vcc
	global_load_dwordx2 v[70:71], v[66:67], off
	v_div_scale_f32 v66, s[4:5], v192, v192, 1.0
	v_rcp_f32_e32 v67, v66
	v_div_scale_f32 v72, vcc, 1.0, v192, 1.0
	v_lshl_add_u64 v[64:65], v[64:65], 0, s[50:51]
	global_load_dwordx2 v[80:81], v[64:65], off offset:16
	global_load_dwordx2 v[82:83], v[64:65], off offset:32
	global_load_dwordx2 v[84:85], v[64:65], off offset:48
	global_load_dwordx2 v[86:87], v[64:65], off offset:64
	global_load_dwordx2 v[88:89], v[64:65], off offset:80
	global_load_dwordx2 v[90:91], v[64:65], off offset:96
	global_load_dwordx2 v[92:93], v[64:65], off offset:112
	global_load_dwordx2 v[94:95], v[64:65], off offset:128
	global_load_dwordx2 v[96:97], v[64:65], off offset:144
	global_load_dwordx2 v[98:99], v[64:65], off offset:160
	global_load_dwordx2 v[100:101], v[64:65], off offset:176
	global_load_dwordx2 v[102:103], v[64:65], off offset:192
	global_load_dwordx2 v[104:105], v[64:65], off offset:208
	global_load_dwordx2 v[106:107], v[64:65], off offset:224
	global_load_dwordx2 v[108:109], v[64:65], off offset:240
	v_fma_f32 v73, -v66, v67, 1.0
	v_fmac_f32_e32 v67, v73, v67
	v_mul_f32_e32 v73, v72, v67
	v_fma_f32 v74, -v66, v73, v72
	v_fmac_f32_e32 v73, v74, v67
	v_fma_f32 v66, -v66, v73, v72
	v_div_fmas_f32 v66, v66, v67, v73
	v_div_fixup_f32 v66, v66, v192, 1.0
	v_mul_f32_e32 v48, v48, v66
	v_mul_f32_e32 v49, v49, v66
	v_mul_f32_e32 v50, v50, v66
	v_mul_f32_e32 v51, v51, v66
	s_mov_b32 s4, 0x17201000
	v_mul_f32_e32 v52, v52, v66
	v_mul_f32_e32 v54, v54, v66
	v_mul_f32_e32 v55, v55, v66
	v_mul_f32_e32 v53, v53, v66
	v_mul_f32_e32 v32, v32, v66
	v_mul_f32_e32 v33, v33, v66
	v_mul_f32_e32 v34, v34, v66
	v_mul_f32_e32 v35, v35, v66
	v_mul_f32_e32 v36, v36, v66
	v_mul_f32_e32 v37, v37, v66
	v_mul_f32_e32 v38, v38, v66
	v_mul_f32_e32 v39, v39, v66
	v_mul_f32_e32 v16, v16, v66
	v_mul_f32_e32 v17, v17, v66
	v_mul_f32_e32 v18, v18, v66
	v_mul_f32_e32 v19, v19, v66
	v_mul_f32_e32 v20, v20, v66
	v_mul_f32_e32 v21, v21, v66
	v_mul_f32_e32 v22, v22, v66
	v_mul_f32_e32 v23, v23, v66
	v_mul_f32_e32 v0, v0, v66
	v_mul_f32_e32 v1, v1, v66
	v_mul_f32_e32 v2, v2, v66
	v_mul_f32_e32 v3, v3, v66
	v_mul_f32_e32 v4, v4, v66
	v_mul_f32_e32 v5, v5, v66
	v_mul_f32_e32 v6, v6, v66
	v_mul_f32_e32 v7, v7, v66
	s_waitcnt vmcnt(15)
	v_lshlrev_b32_e32 v67, 16, v70
	v_and_b32_e32 v70, 0xffff0000, v70
	v_lshlrev_b32_e32 v72, 16, v71
	v_and_b32_e32 v71, 0xffff0000, v71
	v_mul_f32_e32 v48, v48, v67
	v_mul_f32_e32 v49, v49, v70
	v_mul_f32_e32 v50, v50, v72
	v_mul_f32_e32 v51, v51, v71
	v_cvt_pk_bf16_f32 v48, v48, v49
	v_cvt_pk_bf16_f32 v49, v50, v51
	v_lshl_add_u64 v[70:71], s[0:1], 0, v[160:161]
	v_lshl_add_u64 v[70:71], v[70:71], 0, s[2:3]
	v_lshl_add_u64 v[68:69], v[70:71], 0, v[68:69]
	v_add_co_u32_e32 v70, vcc, s4, v68
	s_mov_b64 s[0:1], 0
	s_nop 0
	v_addc_co_u32_e32 v71, vcc, 0, v69, vcc
	global_store_dwordx2 v[70:71], v[48:49], off offset:2048
	s_waitcnt vmcnt(15)
	v_mov_b32_e32 v50, v80
	v_mov_b32_e32 v51, v81
	v_lshlrev_b32_e32 v48, 16, v50
	v_and_b32_e32 v49, 0xffff0000, v50
	v_lshlrev_b32_e32 v50, 16, v51
	v_and_b32_e32 v51, 0xffff0000, v51
	v_mul_f32_e32 v48, v52, v48
	v_mul_f32_e32 v52, v54, v50
	v_mul_f32_e32 v51, v55, v51
	v_mul_f32_e32 v49, v53, v49
	v_cvt_pk_bf16_f32 v50, v48, v49
	v_cvt_pk_bf16_f32 v51, v52, v51
	v_lshl_add_u64 v[48:49], v[68:69], 0, s[52:53]
	v_mul_f32_e32 v54, v56, v66
	v_mul_f32_e32 v55, v57, v66
	v_mul_f32_e32 v56, v58, v66
	v_mul_f32_e32 v57, v59, v66
	global_store_dwordx2 v[48:49], v[50:51], off offset:16
	s_waitcnt vmcnt(15)
	v_mov_b32_e32 v52, v82
	v_mov_b32_e32 v53, v83
	v_lshlrev_b32_e32 v50, 16, v52
	v_and_b32_e32 v51, 0xffff0000, v52
	v_lshlrev_b32_e32 v52, 16, v53
	v_and_b32_e32 v53, 0xffff0000, v53
	v_mul_f32_e32 v50, v54, v50
	v_mul_f32_e32 v51, v55, v51
	v_mul_f32_e32 v52, v56, v52
	v_mul_f32_e32 v53, v57, v53
	v_cvt_pk_bf16_f32 v50, v50, v51
	v_cvt_pk_bf16_f32 v51, v52, v53
	v_mul_f32_e32 v54, v60, v66
	v_mul_f32_e32 v55, v61, v66
	v_mul_f32_e32 v56, v62, v66
	v_mul_f32_e32 v57, v63, v66
	global_store_dwordx2 v[48:49], v[50:51], off offset:32
	s_waitcnt vmcnt(15)
	v_mov_b32_e32 v52, v84
	v_mov_b32_e32 v53, v85
	v_lshlrev_b32_e32 v50, 16, v52
	v_and_b32_e32 v51, 0xffff0000, v52
	v_lshlrev_b32_e32 v52, 16, v53
	v_and_b32_e32 v53, 0xffff0000, v53
	v_mul_f32_e32 v50, v54, v50
	v_mul_f32_e32 v51, v55, v51
	v_mul_f32_e32 v52, v56, v52
	v_mul_f32_e32 v53, v57, v53
	v_cvt_pk_bf16_f32 v50, v50, v51
	v_cvt_pk_bf16_f32 v51, v52, v53
	s_nop 0
	global_store_dwordx2 v[48:49], v[50:51], off offset:48
	s_waitcnt vmcnt(15)
	v_mov_b32_e32 v52, v86
	v_mov_b32_e32 v53, v87
	v_lshlrev_b32_e32 v50, 16, v52
	v_and_b32_e32 v51, 0xffff0000, v52
	v_lshlrev_b32_e32 v52, 16, v53
	v_and_b32_e32 v53, 0xffff0000, v53
	v_mul_f32_e32 v32, v32, v50
	v_mul_f32_e32 v33, v33, v51
	v_mul_f32_e32 v34, v34, v52
	v_mul_f32_e32 v35, v35, v53
	v_cvt_pk_bf16_f32 v32, v32, v33
	v_cvt_pk_bf16_f32 v33, v34, v35
	s_nop 0
	global_store_dwordx2 v[48:49], v[32:33], off offset:64
	s_waitcnt vmcnt(15)
; __device__ __forceinline__ unsigned cvt_pk_bf16(float lo, float hi) { unsigned r; asm volatile("v_cvt_pk_bf16_f32 %0, %1, %2" : "=v"(r) : "v"(lo), "v"(hi)); return r; }
;     template <class T> __device__ __forceinline__ T* w(size_t off) const { return (T*)(pp->ws + off); }
; __device__ __forceinline__ float bf2f(unsigned b) { return __uint_as_float(b << 16); }
; __device__ __forceinline__ void dsa_attn_unit(const Ctx& c, int l, int b, int kvh, int qb64) {
;     ...
;     const float inv = 1.0f / l_run;
;     const bf16* ZC = c.w<bf16>(WS_ZC) + (size_t)row * 1024 + hq * 128;
;     bf16* MX = c.w<bf16>(WS_MIX) + (size_t)row * DM + 3072 + hq * 128;
; #pragma unroll
;     for (int mt = 0; mt < 4; ++mt)
; #pragma unroll
;         for (int v4 = 0; v4 < 4; ++v4) {
;             const int d = 32 * mt + 8 * v4 + 4 * hf;
;             const u32x2 z = *(const u32x2*)(ZC + d);
;             u32x2 w;
;             w.x = pg8::cvt_pk_bf16(O[mt][4 * v4 + 0] * inv * bf2f(z.x & 0xffffu), O[mt][4 * v4 + 1] * inv * bf2f(z.x >> 16));
;             w.y = pg8::cvt_pk_bf16(O[mt][4 * v4 + 2] * inv * bf2f(z.y & 0xffffu), O[mt][4 * v4 + 3] * inv * bf2f(z.y >> 16));
;             *(u32x2*)(MX + d) = w;
;         }
	v_mov_b32_e32 v34, v88
	v_mov_b32_e32 v35, v89
	v_lshlrev_b32_e32 v32, 16, v34
	v_and_b32_e32 v33, 0xffff0000, v34
	v_lshlrev_b32_e32 v34, 16, v35
	v_and_b32_e32 v35, 0xffff0000, v35
	v_mul_f32_e32 v32, v36, v32
	v_mul_f32_e32 v33, v37, v33
	v_mul_f32_e32 v34, v38, v34
	v_mul_f32_e32 v35, v39, v35
	v_cvt_pk_bf16_f32 v32, v32, v33
	v_cvt_pk_bf16_f32 v33, v34, v35
	v_mul_f32_e32 v36, v40, v66
	v_mul_f32_e32 v37, v41, v66
	v_mul_f32_e32 v38, v42, v66
	v_mul_f32_e32 v39, v43, v66
	global_store_dwordx2 v[48:49], v[32:33], off offset:80
	s_waitcnt vmcnt(15)
	v_mov_b32_e32 v34, v90
	v_mov_b32_e32 v35, v91
	v_lshlrev_b32_e32 v32, 16, v34
	v_and_b32_e32 v33, 0xffff0000, v34
	v_lshlrev_b32_e32 v34, 16, v35
	v_and_b32_e32 v35, 0xffff0000, v35
	v_mul_f32_e32 v32, v36, v32
	v_mul_f32_e32 v33, v37, v33
	v_mul_f32_e32 v34, v38, v34
	v_mul_f32_e32 v35, v39, v35
	v_cvt_pk_bf16_f32 v32, v32, v33
	v_cvt_pk_bf16_f32 v33, v34, v35
	v_mul_f32_e32 v36, v44, v66
	v_mul_f32_e32 v37, v45, v66
	v_mul_f32_e32 v38, v46, v66
	v_mul_f32_e32 v39, v47, v66
	global_store_dwordx2 v[48:49], v[32:33], off offset:96
	s_waitcnt vmcnt(15)
	v_mov_b32_e32 v34, v92
	v_mov_b32_e32 v35, v93
	v_lshlrev_b32_e32 v32, 16, v34
	v_and_b32_e32 v33, 0xffff0000, v34
	v_lshlrev_b32_e32 v34, 16, v35
	v_and_b32_e32 v35, 0xffff0000, v35
	v_mul_f32_e32 v32, v36, v32
	v_mul_f32_e32 v33, v37, v33
	v_mul_f32_e32 v34, v38, v34
	v_mul_f32_e32 v35, v39, v35
	v_cvt_pk_bf16_f32 v32, v32, v33
	v_cvt_pk_bf16_f32 v33, v34, v35
	s_nop 0
	global_store_dwordx2 v[48:49], v[32:33], off offset:112
	s_waitcnt vmcnt(15)
	v_mov_b32_e32 v34, v94
	v_mov_b32_e32 v35, v95
	v_lshlrev_b32_e32 v32, 16, v34
	v_and_b32_e32 v33, 0xffff0000, v34
	v_lshlrev_b32_e32 v34, 16, v35
	v_and_b32_e32 v35, 0xffff0000, v35
	v_mul_f32_e32 v16, v16, v32
	v_mul_f32_e32 v17, v17, v33
	v_mul_f32_e32 v18, v18, v34
	v_mul_f32_e32 v19, v19, v35
	v_cvt_pk_bf16_f32 v16, v16, v17
	v_cvt_pk_bf16_f32 v17, v18, v19
	s_nop 0
	global_store_dwordx2 v[48:49], v[16:17], off offset:128
	s_waitcnt vmcnt(15)
	v_mov_b32_e32 v18, v96
	v_mov_b32_e32 v19, v97
	v_lshlrev_b32_e32 v16, 16, v18
	v_and_b32_e32 v17, 0xffff0000, v18
	v_lshlrev_b32_e32 v18, 16, v19
	v_and_b32_e32 v19, 0xffff0000, v19
	v_mul_f32_e32 v16, v20, v16
	v_mul_f32_e32 v17, v21, v17
	v_mul_f32_e32 v18, v22, v18
	v_mul_f32_e32 v19, v23, v19
	v_cvt_pk_bf16_f32 v16, v16, v17
	v_cvt_pk_bf16_f32 v17, v18, v19
	v_mul_f32_e32 v20, v24, v66
	v_mul_f32_e32 v21, v25, v66
	v_mul_f32_e32 v22, v26, v66
	v_mul_f32_e32 v23, v27, v66
	global_store_dwordx2 v[48:49], v[16:17], off offset:144
	s_waitcnt vmcnt(15)
	v_mov_b32_e32 v18, v98
	v_mov_b32_e32 v19, v99
	v_lshlrev_b32_e32 v16, 16, v18
	v_and_b32_e32 v17, 0xffff0000, v18
	v_lshlrev_b32_e32 v18, 16, v19
	v_and_b32_e32 v19, 0xffff0000, v19
	v_mul_f32_e32 v16, v20, v16
	v_mul_f32_e32 v17, v21, v17
	v_mul_f32_e32 v18, v22, v18
	v_mul_f32_e32 v19, v23, v19
	v_cvt_pk_bf16_f32 v16, v16, v17
	v_cvt_pk_bf16_f32 v17, v18, v19
	v_mul_f32_e32 v20, v28, v66
	v_mul_f32_e32 v21, v29, v66
	v_mul_f32_e32 v22, v30, v66
	v_mul_f32_e32 v23, v31, v66
	global_store_dwordx2 v[48:49], v[16:17], off offset:160
	s_waitcnt vmcnt(15)
	v_mov_b32_e32 v18, v100
	v_mov_b32_e32 v19, v101
	v_lshlrev_b32_e32 v16, 16, v18
	v_and_b32_e32 v17, 0xffff0000, v18
	v_lshlrev_b32_e32 v18, 16, v19
	v_and_b32_e32 v19, 0xffff0000, v19
	v_mul_f32_e32 v16, v20, v16
	v_mul_f32_e32 v17, v21, v17
	v_mul_f32_e32 v18, v22, v18
	v_mul_f32_e32 v19, v23, v19
	v_cvt_pk_bf16_f32 v16, v16, v17
	v_cvt_pk_bf16_f32 v17, v18, v19
	s_nop 0
	global_store_dwordx2 v[48:49], v[16:17], off offset:176
	s_waitcnt vmcnt(15)
	v_mov_b32_e32 v18, v102
	v_mov_b32_e32 v19, v103
	v_lshlrev_b32_e32 v16, 16, v18
	v_and_b32_e32 v17, 0xffff0000, v18
	v_lshlrev_b32_e32 v18, 16, v19
	v_and_b32_e32 v19, 0xffff0000, v19
	v_mul_f32_e32 v0, v0, v16
	v_mul_f32_e32 v1, v1, v17
	v_mul_f32_e32 v2, v2, v18
	v_mul_f32_e32 v3, v3, v19
	v_cvt_pk_bf16_f32 v0, v0, v1
	v_cvt_pk_bf16_f32 v1, v2, v3
	s_nop 0
	global_store_dwordx2 v[48:49], v[0:1], off offset:192
	s_waitcnt vmcnt(15)
	v_mov_b32_e32 v2, v104
	v_mov_b32_e32 v3, v105
	v_lshlrev_b32_e32 v0, 16, v2
	v_and_b32_e32 v1, 0xffff0000, v2
	v_lshlrev_b32_e32 v2, 16, v3
	v_and_b32_e32 v3, 0xffff0000, v3
	v_mul_f32_e32 v0, v4, v0
	v_mul_f32_e32 v1, v5, v1
	v_mul_f32_e32 v2, v6, v2
	v_mul_f32_e32 v3, v7, v3
	v_cvt_pk_bf16_f32 v0, v0, v1
	v_cvt_pk_bf16_f32 v1, v2, v3
	v_mul_f32_e32 v4, v8, v66
	v_mul_f32_e32 v5, v9, v66
	v_mul_f32_e32 v6, v10, v66
	v_mul_f32_e32 v7, v11, v66
	global_store_dwordx2 v[48:49], v[0:1], off offset:208
	s_waitcnt vmcnt(15)
	v_mov_b32_e32 v2, v106
	v_mov_b32_e32 v3, v107
	v_lshlrev_b32_e32 v0, 16, v2
	v_and_b32_e32 v1, 0xffff0000, v2
	v_lshlrev_b32_e32 v2, 16, v3
	v_and_b32_e32 v3, 0xffff0000, v3
	v_mul_f32_e32 v0, v4, v0
	v_mul_f32_e32 v1, v5, v1
	v_mul_f32_e32 v2, v6, v2
	v_mul_f32_e32 v3, v7, v3
	v_cvt_pk_bf16_f32 v0, v0, v1
	v_cvt_pk_bf16_f32 v1, v2, v3
	v_mul_f32_e32 v4, v12, v66
	v_mul_f32_e32 v5, v13, v66
	global_store_dwordx2 v[48:49], v[0:1], off offset:224
	v_mul_f32_e32 v6, v14, v66
	v_mul_f32_e32 v7, v15, v66
	s_waitcnt vmcnt(15)
	v_mov_b32_e32 v2, v108
	v_mov_b32_e32 v3, v109
	v_lshlrev_b32_e32 v0, 16, v2
	v_and_b32_e32 v1, 0xffff0000, v2
	v_lshlrev_b32_e32 v2, 16, v3
	v_and_b32_e32 v3, 0xffff0000, v3
	v_mul_f32_e32 v0, v4, v0
	v_mul_f32_e32 v1, v5, v1
	v_mul_f32_e32 v2, v6, v2
	v_mul_f32_e32 v3, v7, v3
	v_cvt_pk_bf16_f32 v0, v0, v1
	v_cvt_pk_bf16_f32 v1, v2, v3
	global_store_dwordx2 v[48:49], v[0:1], off offset:240

; __device__ __forceinline__ unsigned cvt_pk_bf16(float lo, float hi) { unsigned r; asm volatile("v_cvt_pk_bf16_f32 %0, %1, %2" : "=v"(r) : "v"(lo), "v"(hi)); return r; }
;     template <class T> __device__ __forceinline__ T* w(size_t off) const { return (T*)(pp->ws + off); }
; __device__ __forceinline__ float bf2f(unsigned b) { return __uint_as_float(b << 16); }
; __device__ __forceinline__ void dsa_attn_unit(const Ctx& c, int l, int b, int kvh, int qb64) {
;     ...
;     const float inv = 1.0f / l_run;
;     const bf16* ZC = c.w<bf16>(WS_ZC) + (size_t)row * 1024 + hq * 128;
;     bf16* MX = c.w<bf16>(WS_MIX) + (size_t)row * DM + 3072 + hq * 128;
; #pragma unroll
;     for (int mt = 0; mt < 4; ++mt)
; #pragma unroll
;         for (int v4 = 0; v4 < 4; ++v4) {
;             const int d = 32 * mt + 8 * v4 + 4 * hf;
;             const u32x2 z = *(const u32x2*)(ZC + d);
;             u32x2 w;
;             w.x = pg8::cvt_pk_bf16(O[mt][4 * v4 + 0] * inv * bf2f(z.x & 0xffffu), O[mt][4 * v4 + 1] * inv * bf2f(z.x >> 16));
;             w.y = pg8::cvt_pk_bf16(O[mt][4 * v4 + 2] * inv * bf2f(z.y & 0xffffu), O[mt][4 * v4 + 3] * inv * bf2f(z.y >> 16));
;             *(u32x2*)(MX + d) = w;
;         }
.LBB0_2901:
	v_lshl_add_u64 v[64:65], v[160:161], 1, s[2:3]
	s_lshl_b64 s[4:5], s[4:5], 1
	v_ashrrev_i32_e32 v169, 31, v168
	v_lshl_add_u64 v[64:65], v[64:65], 0, s[4:5]
	v_lshlrev_b64 v[66:67], 1, v[168:169]
	v_lshl_add_u64 v[64:65], v[64:65], 0, v[66:67]
	v_add_co_u32_e32 v68, vcc, s61, v64
	v_div_scale_f32 v70, s[6:7], v213, v213, 1.0
	s_nop 0
	v_addc_co_u32_e32 v69, vcc, 0, v65, vcc
	global_load_dwordx2 v[68:69], v[68:69], off
	v_rcp_f32_e32 v71, v70
	v_div_scale_f32 v72, vcc, 1.0, v213, 1.0
	v_lshl_add_u64 v[64:65], v[64:65], 0, s[22:23]
	global_load_dwordx2 v[80:81], v[64:65], off offset:16
	global_load_dwordx2 v[82:83], v[64:65], off offset:32
	global_load_dwordx2 v[84:85], v[64:65], off offset:48
	global_load_dwordx2 v[86:87], v[64:65], off offset:64
	global_load_dwordx2 v[88:89], v[64:65], off offset:80
	global_load_dwordx2 v[90:91], v[64:65], off offset:96
	global_load_dwordx2 v[92:93], v[64:65], off offset:112
	global_load_dwordx2 v[94:95], v[64:65], off offset:128
	global_load_dwordx2 v[96:97], v[64:65], off offset:144
	global_load_dwordx2 v[98:99], v[64:65], off offset:160
	global_load_dwordx2 v[100:101], v[64:65], off offset:176
	global_load_dwordx2 v[102:103], v[64:65], off offset:192
	global_load_dwordx2 v[104:105], v[64:65], off offset:208
	global_load_dwordx2 v[106:107], v[64:65], off offset:224
	global_load_dwordx2 v[108:109], v[64:65], off offset:240
	v_fma_f32 v73, -v70, v71, 1.0
	v_fmac_f32_e32 v71, v73, v71
	v_mul_f32_e32 v73, v72, v71
	v_fma_f32 v74, -v70, v73, v72
	v_fmac_f32_e32 v73, v74, v71
	v_fma_f32 v70, -v70, v73, v72
	v_div_fmas_f32 v70, v70, v71, v73
	v_div_fixup_f32 v70, v70, v213, 1.0
	v_mul_f32_e32 v48, v48, v70
	v_mul_f32_e32 v49, v49, v70
	v_mul_f32_e32 v50, v50, v70
	v_mul_f32_e32 v51, v51, v70
	v_lshlrev_b32_e32 v160, 13, v166
	v_mul_f32_e32 v52, v52, v70
	v_mul_f32_e32 v54, v54, v70
	v_mul_f32_e32 v55, v55, v70
	v_mul_f32_e32 v53, v53, v70
	v_mul_f32_e32 v32, v32, v70
	v_mul_f32_e32 v33, v33, v70
	v_mul_f32_e32 v34, v34, v70
	v_mul_f32_e32 v35, v35, v70
	v_mul_f32_e32 v36, v36, v70
	v_mul_f32_e32 v37, v37, v70
	v_mul_f32_e32 v38, v38, v70
	v_mul_f32_e32 v39, v39, v70
	v_mul_f32_e32 v16, v16, v70
	v_mul_f32_e32 v17, v17, v70
	v_mul_f32_e32 v18, v18, v70
	v_mul_f32_e32 v19, v19, v70
	v_mul_f32_e32 v20, v20, v70
	v_mul_f32_e32 v21, v21, v70
	v_mul_f32_e32 v22, v22, v70
	v_mul_f32_e32 v23, v23, v70
	v_mul_f32_e32 v0, v0, v70
	v_mul_f32_e32 v1, v1, v70
	v_mul_f32_e32 v2, v2, v70
	v_mul_f32_e32 v3, v3, v70
	v_mul_f32_e32 v4, v4, v70
	v_mul_f32_e32 v5, v5, v70
	v_mul_f32_e32 v6, v6, v70
	v_mul_f32_e32 v7, v7, v70
	s_waitcnt vmcnt(15)
	v_lshlrev_b32_e32 v71, 16, v68
	v_and_b32_e32 v68, 0xffff0000, v68
	v_lshlrev_b32_e32 v72, 16, v69
	v_and_b32_e32 v69, 0xffff0000, v69
	v_mul_f32_e32 v48, v48, v71
	v_mul_f32_e32 v49, v49, v68
	v_mul_f32_e32 v50, v50, v72
	v_mul_f32_e32 v51, v51, v69
	v_cvt_pk_bf16_f32 v48, v48, v49
	v_cvt_pk_bf16_f32 v49, v50, v51
	v_lshl_add_u64 v[68:69], s[2:3], 0, v[160:161]
	v_lshl_add_u64 v[68:69], v[68:69], 0, s[4:5]
	v_lshl_add_u64 v[66:67], v[68:69], 0, v[66:67]
	v_add_co_u32_e32 v68, vcc, s62, v66
	s_mov_b64 s[2:3], 0
	s_nop 0
	v_addc_co_u32_e32 v69, vcc, 0, v67, vcc
	global_store_dwordx2 v[68:69], v[48:49], off offset:2048
	s_waitcnt vmcnt(15)
	v_mov_b32_e32 v50, v80
	v_mov_b32_e32 v51, v81
	v_lshlrev_b32_e32 v48, 16, v50
	v_and_b32_e32 v49, 0xffff0000, v50
	v_lshlrev_b32_e32 v50, 16, v51
	v_and_b32_e32 v51, 0xffff0000, v51
	v_mul_f32_e32 v48, v52, v48
	v_mul_f32_e32 v52, v54, v50
	v_mul_f32_e32 v51, v55, v51
	v_mul_f32_e32 v49, v53, v49
	v_cvt_pk_bf16_f32 v50, v48, v49
	v_cvt_pk_bf16_f32 v51, v52, v51
	v_lshl_add_u64 v[48:49], v[66:67], 0, s[24:25]
	v_mul_f32_e32 v54, v56, v70
	v_mul_f32_e32 v55, v57, v70
	v_mul_f32_e32 v56, v58, v70
	v_mul_f32_e32 v57, v59, v70
	global_store_dwordx2 v[48:49], v[50:51], off offset:16
	s_waitcnt vmcnt(15)
	v_mov_b32_e32 v52, v82
	v_mov_b32_e32 v53, v83
	v_lshlrev_b32_e32 v50, 16, v52
	v_and_b32_e32 v51, 0xffff0000, v52
	v_lshlrev_b32_e32 v52, 16, v53
	v_and_b32_e32 v53, 0xffff0000, v53
	v_mul_f32_e32 v50, v54, v50
	v_mul_f32_e32 v51, v55, v51
	v_mul_f32_e32 v52, v56, v52
	v_mul_f32_e32 v53, v57, v53
	v_cvt_pk_bf16_f32 v50, v50, v51
	v_cvt_pk_bf16_f32 v51, v52, v53
	v_mul_f32_e32 v54, v60, v70
	v_mul_f32_e32 v55, v61, v70
	v_mul_f32_e32 v56, v62, v70
	v_mul_f32_e32 v57, v63, v70
	global_store_dwordx2 v[48:49], v[50:51], off offset:32
	s_waitcnt vmcnt(15)
	v_mov_b32_e32 v52, v84
	v_mov_b32_e32 v53, v85
	v_lshlrev_b32_e32 v50, 16, v52
	v_and_b32_e32 v51, 0xffff0000, v52
	v_lshlrev_b32_e32 v52, 16, v53
	v_and_b32_e32 v53, 0xffff0000, v53
	v_mul_f32_e32 v50, v54, v50
	v_mul_f32_e32 v51, v55, v51
	v_mul_f32_e32 v52, v56, v52
	v_mul_f32_e32 v53, v57, v53
	v_cvt_pk_bf16_f32 v50, v50, v51
	v_cvt_pk_bf16_f32 v51, v52, v53
	s_nop 0
	global_store_dwordx2 v[48:49], v[50:51], off offset:48
	s_waitcnt vmcnt(15)
	v_mov_b32_e32 v52, v86
	v_mov_b32_e32 v53, v87
	v_lshlrev_b32_e32 v50, 16, v52
	v_and_b32_e32 v51, 0xffff0000, v52
	v_lshlrev_b32_e32 v52, 16, v53
	v_and_b32_e32 v53, 0xffff0000, v53
	v_mul_f32_e32 v32, v32, v50
	v_mul_f32_e32 v33, v33, v51
	v_mul_f32_e32 v34, v34, v52
	v_mul_f32_e32 v35, v35, v53
	v_cvt_pk_bf16_f32 v32, v32, v33
	v_cvt_pk_bf16_f32 v33, v34, v35
	s_nop 0
	global_store_dwordx2 v[48:49], v[32:33], off offset:64
	s_waitcnt vmcnt(15)
; __device__ __forceinline__ unsigned cvt_pk_bf16(float lo, float hi) { unsigned r; asm volatile("v_cvt_pk_bf16_f32 %0, %1, %2" : "=v"(r) : "v"(lo), "v"(hi)); return r; }
;     template <class T> __device__ __forceinline__ T* w(size_t off) const { return (T*)(pp->ws + off); }
; __device__ __forceinline__ float bf2f(unsigned b) { return __uint_as_float(b << 16); }
; __device__ __forceinline__ void dsa_attn_unit(const Ctx& c, int l, int b, int kvh, int qb64) {
;     ...
;     const float inv = 1.0f / l_run;
;     const bf16* ZC = c.w<bf16>(WS_ZC) + (size_t)row * 1024 + hq * 128;
;     bf16* MX = c.w<bf16>(WS_MIX) + (size_t)row * DM + 3072 + hq * 128;
; #pragma unroll
;     for (int mt = 0; mt < 4; ++mt)
; #pragma unroll
;         for (int v4 = 0; v4 < 4; ++v4) {
;             const int d = 32 * mt + 8 * v4 + 4 * hf;
;             const u32x2 z = *(const u32x2*)(ZC + d);
;             u32x2 w;
;             w.x = pg8::cvt_pk_bf16(O[mt][4 * v4 + 0] * inv * bf2f(z.x & 0xffffu), O[mt][4 * v4 + 1] * inv * bf2f(z.x >> 16));
;             w.y = pg8::cvt_pk_bf16(O[mt][4 * v4 + 2] * inv * bf2f(z.y & 0xffffu), O[mt][4 * v4 + 3] * inv * bf2f(z.y >> 16));
;             *(u32x2*)(MX + d) = w;
;         }
	v_mov_b32_e32 v34, v88
	v_mov_b32_e32 v35, v89
	v_lshlrev_b32_e32 v32, 16, v34
	v_and_b32_e32 v33, 0xffff0000, v34
	v_lshlrev_b32_e32 v34, 16, v35
	v_and_b32_e32 v35, 0xffff0000, v35
	v_mul_f32_e32 v32, v36, v32
	v_mul_f32_e32 v33, v37, v33
	v_mul_f32_e32 v34, v38, v34
	v_mul_f32_e32 v35, v39, v35
	v_cvt_pk_bf16_f32 v32, v32, v33
	v_cvt_pk_bf16_f32 v33, v34, v35
	v_mul_f32_e32 v36, v40, v70
	v_mul_f32_e32 v37, v41, v70
	v_mul_f32_e32 v38, v42, v70
	v_mul_f32_e32 v39, v43, v70
	global_store_dwordx2 v[48:49], v[32:33], off offset:80
	s_waitcnt vmcnt(15)
	v_mov_b32_e32 v34, v90
	v_mov_b32_e32 v35, v91
	v_lshlrev_b32_e32 v32, 16, v34
	v_and_b32_e32 v33, 0xffff0000, v34
	v_lshlrev_b32_e32 v34, 16, v35
	v_and_b32_e32 v35, 0xffff0000, v35
	v_mul_f32_e32 v32, v36, v32
	v_mul_f32_e32 v33, v37, v33
	v_mul_f32_e32 v34, v38, v34
	v_mul_f32_e32 v35, v39, v35
	v_cvt_pk_bf16_f32 v32, v32, v33
	v_cvt_pk_bf16_f32 v33, v34, v35
	v_mul_f32_e32 v36, v44, v70
	v_mul_f32_e32 v37, v45, v70
	v_mul_f32_e32 v38, v46, v70
	v_mul_f32_e32 v39, v47, v70
	global_store_dwordx2 v[48:49], v[32:33], off offset:96
	s_waitcnt vmcnt(15)
	v_mov_b32_e32 v34, v92
	v_mov_b32_e32 v35, v93
	v_lshlrev_b32_e32 v32, 16, v34
	v_and_b32_e32 v33, 0xffff0000, v34
	v_lshlrev_b32_e32 v34, 16, v35
	v_and_b32_e32 v35, 0xffff0000, v35
	v_mul_f32_e32 v32, v36, v32
	v_mul_f32_e32 v33, v37, v33
	v_mul_f32_e32 v34, v38, v34
	v_mul_f32_e32 v35, v39, v35
	v_cvt_pk_bf16_f32 v32, v32, v33
	v_cvt_pk_bf16_f32 v33, v34, v35
	s_nop 0
	global_store_dwordx2 v[48:49], v[32:33], off offset:112
	s_waitcnt vmcnt(15)
	v_mov_b32_e32 v34, v94
	v_mov_b32_e32 v35, v95
	v_lshlrev_b32_e32 v32, 16, v34
	v_and_b32_e32 v33, 0xffff0000, v34
	v_lshlrev_b32_e32 v34, 16, v35
	v_and_b32_e32 v35, 0xffff0000, v35
	v_mul_f32_e32 v16, v16, v32
	v_mul_f32_e32 v17, v17, v33
	v_mul_f32_e32 v18, v18, v34
	v_mul_f32_e32 v19, v19, v35
	v_cvt_pk_bf16_f32 v16, v16, v17
	v_cvt_pk_bf16_f32 v17, v18, v19
	s_nop 0
	global_store_dwordx2 v[48:49], v[16:17], off offset:128
	s_waitcnt vmcnt(15)
	v_mov_b32_e32 v18, v96
	v_mov_b32_e32 v19, v97
	v_lshlrev_b32_e32 v16, 16, v18
	v_and_b32_e32 v17, 0xffff0000, v18
	v_lshlrev_b32_e32 v18, 16, v19
	v_and_b32_e32 v19, 0xffff0000, v19
	v_mul_f32_e32 v16, v20, v16
	v_mul_f32_e32 v17, v21, v17
	v_mul_f32_e32 v18, v22, v18
	v_mul_f32_e32 v19, v23, v19
	v_cvt_pk_bf16_f32 v16, v16, v17
	v_cvt_pk_bf16_f32 v17, v18, v19
	v_mul_f32_e32 v20, v24, v70
	v_mul_f32_e32 v21, v25, v70
	v_mul_f32_e32 v22, v26, v70
	v_mul_f32_e32 v23, v27, v70
	global_store_dwordx2 v[48:49], v[16:17], off offset:144
	s_waitcnt vmcnt(15)
	v_mov_b32_e32 v18, v98
	v_mov_b32_e32 v19, v99
	v_lshlrev_b32_e32 v16, 16, v18
	v_and_b32_e32 v17, 0xffff0000, v18
	v_lshlrev_b32_e32 v18, 16, v19
	v_and_b32_e32 v19, 0xffff0000, v19
	v_mul_f32_e32 v16, v20, v16
	v_mul_f32_e32 v17, v21, v17
	v_mul_f32_e32 v18, v22, v18
	v_mul_f32_e32 v19, v23, v19
	v_cvt_pk_bf16_f32 v16, v16, v17
	v_cvt_pk_bf16_f32 v17, v18, v19
	v_mul_f32_e32 v20, v28, v70
	v_mul_f32_e32 v21, v29, v70
	v_mul_f32_e32 v22, v30, v70
	v_mul_f32_e32 v23, v31, v70
	global_store_dwordx2 v[48:49], v[16:17], off offset:160
	s_waitcnt vmcnt(15)
	v_mov_b32_e32 v18, v100
	v_mov_b32_e32 v19, v101
	v_lshlrev_b32_e32 v16, 16, v18
	v_and_b32_e32 v17, 0xffff0000, v18
	v_lshlrev_b32_e32 v18, 16, v19
	v_and_b32_e32 v19, 0xffff0000, v19
	v_mul_f32_e32 v16, v20, v16
	v_mul_f32_e32 v17, v21, v17
	v_mul_f32_e32 v18, v22, v18
	v_mul_f32_e32 v19, v23, v19
	v_cvt_pk_bf16_f32 v16, v16, v17
	v_cvt_pk_bf16_f32 v17, v18, v19
	s_nop 0
	global_store_dwordx2 v[48:49], v[16:17], off offset:176
	s_waitcnt vmcnt(15)
	v_mov_b32_e32 v18, v102
	v_mov_b32_e32 v19, v103
	v_lshlrev_b32_e32 v16, 16, v18
	v_and_b32_e32 v17, 0xffff0000, v18
	v_lshlrev_b32_e32 v18, 16, v19
	v_and_b32_e32 v19, 0xffff0000, v19
	v_mul_f32_e32 v0, v0, v16
	v_mul_f32_e32 v1, v1, v17
	v_mul_f32_e32 v2, v2, v18
	v_mul_f32_e32 v3, v3, v19
	v_cvt_pk_bf16_f32 v0, v0, v1
	v_cvt_pk_bf16_f32 v1, v2, v3
	s_nop 0
	global_store_dwordx2 v[48:49], v[0:1], off offset:192
	s_waitcnt vmcnt(15)
	v_mov_b32_e32 v2, v104
	v_mov_b32_e32 v3, v105
	v_lshlrev_b32_e32 v0, 16, v2
	v_and_b32_e32 v1, 0xffff0000, v2
	v_lshlrev_b32_e32 v2, 16, v3
	v_and_b32_e32 v3, 0xffff0000, v3
	v_mul_f32_e32 v0, v4, v0
	v_mul_f32_e32 v1, v5, v1
	v_mul_f32_e32 v2, v6, v2
	v_mul_f32_e32 v3, v7, v3
	v_cvt_pk_bf16_f32 v0, v0, v1
	v_cvt_pk_bf16_f32 v1, v2, v3
	v_mul_f32_e32 v4, v8, v70
	v_mul_f32_e32 v5, v9, v70
	v_mul_f32_e32 v6, v10, v70
	v_mul_f32_e32 v7, v11, v70
	global_store_dwordx2 v[48:49], v[0:1], off offset:208
	s_waitcnt vmcnt(15)
	v_mov_b32_e32 v2, v106
	v_mov_b32_e32 v3, v107
	v_lshlrev_b32_e32 v0, 16, v2
	v_and_b32_e32 v1, 0xffff0000, v2
	v_lshlrev_b32_e32 v2, 16, v3
	v_and_b32_e32 v3, 0xffff0000, v3
	v_mul_f32_e32 v0, v4, v0
	v_mul_f32_e32 v1, v5, v1
	v_mul_f32_e32 v2, v6, v2
	v_mul_f32_e32 v3, v7, v3
	v_cvt_pk_bf16_f32 v0, v0, v1
	v_cvt_pk_bf16_f32 v1, v2, v3
	v_mul_f32_e32 v4, v12, v70
	v_mul_f32_e32 v5, v13, v70
	global_store_dwordx2 v[48:49], v[0:1], off offset:224
	v_mul_f32_e32 v6, v14, v70
	v_mul_f32_e32 v7, v15, v70
	s_waitcnt vmcnt(15)
	v_mov_b32_e32 v2, v108
	v_mov_b32_e32 v3, v109
	v_lshlrev_b32_e32 v0, 16, v2
	v_and_b32_e32 v1, 0xffff0000, v2
	v_lshlrev_b32_e32 v2, 16, v3
	v_and_b32_e32 v3, 0xffff0000, v3
	v_mul_f32_e32 v0, v4, v0
	v_mul_f32_e32 v1, v5, v1
	v_mul_f32_e32 v2, v6, v2
	v_mul_f32_e32 v3, v7, v3
	v_cvt_pk_bf16_f32 v0, v0, v1
	v_cvt_pk_bf16_f32 v1, v2, v3
	global_store_dwordx2 v[48:49], v[0:1], off offset:240
